# PH1: each wave takes 8-9 consecutive rows (prefetch row adjacent) instead of rows gw + k*NGW (16 MB apart)
# speedup vs baseline: 1.0023x; 1.0023x over previous
;     ...
;     if (gw < nrows) { const float* s0_ = (gw < ML) ? srcL + (size_t)gw * D : srcC + (size_t)(gw - ML) * D;
; #pragma unroll
;         for (int j = 0; j < 8; ++j) nv[j] = *(const f32x4*)(s0_ + lane * 4 + 256 * j); }
;     for (int m = gw; m < nrows; m += NGW) {
;         float* dst; int mv;
;         if (m < ML) { dst = dstL + (size_t)m * D; mv = (m >= SEQ) ? 1 : 0; }
;         else { dst = dstC + (size_t)(m - ML) * D; mv = 2; }
;         f32x4 v[8];
; #pragma unroll
;         for (int j = 0; j < 8; ++j) v[j] = nv[j];
;         { const int mn = m + NGW;
;           if (mn < nrows) { const float* s1_ = (mn < ML) ? srcL + (size_t)mn * D : srcC + (size_t)(mn - ML) * D;
; #pragma unroll
;               for (int j = 0; j < 8; ++j) nv[j] = *(const f32x4*)(s1_ + lane * 4 + 256 * j); } }
;     ...
;             if (l == 0 && PHON(0)) rowwise(gw, NGW, lane, MT, in.p[0], in.p[2], XL, XC, false, in.p[22], in.p[23], true, modl, 0, 1, AC);
.LBB0_53:
	s_cmp_lt_i32 s72, 2
	s_cselect_b64 s[4:5], -1, 0
	s_cmp_gt_i32 s73, 1
	v_writelane_b32 v246, s68, 31
	s_cselect_b64 s[6:7], -1, 0
	s_and_b64 s[4:5], s[4:5], s[6:7]
	v_writelane_b32 v246, s69, 32
	v_writelane_b32 v246, s70, 33
	v_writelane_b32 v246, s71, 34
	v_writelane_b32 v246, s72, 35
	v_writelane_b32 v246, s73, 36
	s_andn2_b64 vcc, exec, s[4:5]
	v_writelane_b32 v246, s74, 37
	v_writelane_b32 v246, s75, 38
	s_cbranch_vccnz .LBB0_113
	v_readfirstlane_b32 s3, v174
	v_readlane_b32 s2, v246, 0
	s_lshr_b32 s3, s3, 6
	s_lshl_b32 s4, s2, 3
	s_waitcnt lgkmcnt(0)
	s_add_i32 s12, s3, s4
	s_cmpk_gt_i32 s12, 0x41ff
	s_cbranch_scc1 .LBB0_59
	v_readlane_b32 s16, v246, 15
	v_readlane_b32 s17, v246, 16
	v_readlane_b32 s20, v246, 19
	v_readlane_b32 s21, v246, 20
	s_lshl_b32 s4, s74, 3
	s_lshl_b32 s5, s74, 3
	s_movk_i32 s19, 0x4200
	s_cmpk_lg_u32 s74, 0x100
	s_cbranch_scc1 .Lp1_mapdone
	s_mul_i32 s19, s12, 33
	s_add_i32 s19, s19, 33
	s_lshr_b32 s19, s19, 2
	s_mul_i32 s12, s12, 33
	s_lshr_b32 s12, s12, 2
	s_mov_b32 s4, 1
	s_mov_b32 s5, 1
.Lp1_mapdone:
	v_and_b32_e32 v168, 63, v174
	v_lshlrev_b32_e32 v170, 3, v168
	v_lshlrev_b32_e32 v168, 4, v168
	s_mov_b32 s13, -1
	s_add_u32 s24, s70, 0x6700000
	s_addc_u32 s25, s71, 0
	s_add_i32 s8, s12, 0xffffc000
	s_cmpk_lt_i32 s12, 0x4000
	s_cselect_b32 s6, s16, s20
	s_cselect_b32 s7, s17, s21
	s_cselect_b32 s8, s12, s8
	s_lshl_b32 s8, s8, 13
	s_add_u32 s6, s6, s8
	s_addc_u32 s7, s7, 0
	s_add_u32 s10, s6, 0x1000
	s_addc_u32 s11, s7, 0
	global_load_dwordx4 v[0:3], v168, s[6:7]
	global_load_dwordx4 v[4:7], v168, s[6:7] offset:1024
	global_load_dwordx4 v[8:11], v168, s[6:7] offset:2048
	global_load_dwordx4 v[12:15], v168, s[6:7] offset:3072
	global_load_dwordx4 v[16:19], v168, s[10:11]
	global_load_dwordx4 v[20:23], v168, s[10:11] offset:1024
	global_load_dwordx4 v[24:27], v168, s[10:11] offset:2048
	global_load_dwordx4 v[28:31], v168, s[10:11] offset:3072
.Lp1_it0:
	s_waitcnt vmcnt(8)
	s_add_i32 s14, s12, s5
	s_cmp_lt_i32 s14, s19
	s_cbranch_scc0 .Lp1_nopf0
	s_add_i32 s8, s14, 0xffffc000
	s_cmpk_lt_i32 s14, 0x4000
	s_cselect_b32 s6, s16, s20
	s_cselect_b32 s7, s17, s21
	s_cselect_b32 s8, s14, s8
	s_lshl_b32 s8, s8, 13
	s_add_u32 s6, s6, s8
	s_addc_u32 s7, s7, 0
	s_add_u32 s10, s6, 0x1000
	s_addc_u32 s11, s7, 0
	global_load_dwordx4 v[32:35], v168, s[6:7]
	global_load_dwordx4 v[36:39], v168, s[6:7] offset:1024
	global_load_dwordx4 v[40:43], v168, s[6:7] offset:2048
	global_load_dwordx4 v[44:47], v168, s[6:7] offset:3072
	global_load_dwordx4 v[48:51], v168, s[10:11]
	global_load_dwordx4 v[52:55], v168, s[10:11] offset:1024
	global_load_dwordx4 v[56:59], v168, s[10:11] offset:2048
	global_load_dwordx4 v[60:63], v168, s[10:11] offset:3072

; __device__ __forceinline__ unsigned pk2(float lo, float hi) { return f2bf(lo) | (f2bf(hi) << 16); }
;     ...
;         { const int mn = m + NGW;
;           if (mn < nrows) { const float* s1_ = (mn < ML) ? srcL + (size_t)mn * D : srcC + (size_t)(mn - ML) * D;
; #pragma unroll
;               for (int j = 0; j < 8; ++j) nv[j] = *(const f32x4*)(s1_ + lane * 4 + 256 * j); } }
;     ...
;         if (do_mod) {
;             const float* sh = modl + mv * NMOD + shc * D; const float* sc = modl + mv * NMOD + scc * D;
; #pragma unroll
;             for (int j = 0; j < 8; ++j) { const f32x4 s1 = *(const f32x4*)(sc + lane * 4 + 256 * j), h1 = *(const f32x4*)(sh + lane * 4 + 256 * j);
;                 const f32x4 a = v[j] * (s1 + 1.f) + h1; u32x2 o; o.x = pk2(a.x, a.y); o.y = pk2(a.z, a.w);
;                 *(u32x2*)(aout + (size_t)m * D + lane * 4 + 256 * j) = o; }
.Lp1_modok0:
	s_lshl_b32 s18, s12, 12
	s_add_u32 s8, s24, s18
	s_addc_u32 s9, s25, 0
	v_pk_fma_f32 v[160:161], v[0:1], v[96:97], v[128:129]
	v_pk_fma_f32 v[162:163], v[2:3], v[98:99], v[130:131]
	v_cvt_pk_bf16_f32 v164, v160, v161
	v_cvt_pk_bf16_f32 v165, v162, v163
	global_store_dwordx2 v170, v[164:165], s[8:9]
	v_pk_fma_f32 v[160:161], v[4:5], v[100:101], v[132:133]
	v_pk_fma_f32 v[162:163], v[6:7], v[102:103], v[134:135]
	v_cvt_pk_bf16_f32 v164, v160, v161
	v_cvt_pk_bf16_f32 v165, v162, v163
	global_store_dwordx2 v170, v[164:165], s[8:9] offset:512
	v_pk_fma_f32 v[160:161], v[8:9], v[104:105], v[136:137]
	v_pk_fma_f32 v[162:163], v[10:11], v[106:107], v[138:139]
	v_cvt_pk_bf16_f32 v164, v160, v161
	v_cvt_pk_bf16_f32 v165, v162, v163
	global_store_dwordx2 v170, v[164:165], s[8:9] offset:1024
	v_pk_fma_f32 v[160:161], v[12:13], v[108:109], v[140:141]
	v_pk_fma_f32 v[162:163], v[14:15], v[110:111], v[142:143]
	v_cvt_pk_bf16_f32 v164, v160, v161
	v_cvt_pk_bf16_f32 v165, v162, v163
	global_store_dwordx2 v170, v[164:165], s[8:9] offset:1536
	v_pk_fma_f32 v[160:161], v[16:17], v[112:113], v[144:145]
	v_pk_fma_f32 v[162:163], v[18:19], v[114:115], v[146:147]
	v_cvt_pk_bf16_f32 v164, v160, v161
	v_cvt_pk_bf16_f32 v165, v162, v163
	global_store_dwordx2 v170, v[164:165], s[8:9] offset:2048
	v_pk_fma_f32 v[160:161], v[20:21], v[116:117], v[148:149]
	v_pk_fma_f32 v[162:163], v[22:23], v[118:119], v[150:151]
	v_cvt_pk_bf16_f32 v164, v160, v161
	v_cvt_pk_bf16_f32 v165, v162, v163
	global_store_dwordx2 v170, v[164:165], s[8:9] offset:2560
	v_pk_fma_f32 v[160:161], v[24:25], v[120:121], v[152:153]
	v_pk_fma_f32 v[162:163], v[26:27], v[122:123], v[154:155]
	v_cvt_pk_bf16_f32 v164, v160, v161
	v_cvt_pk_bf16_f32 v165, v162, v163
	global_store_dwordx2 v170, v[164:165], s[8:9] offset:3072
	v_pk_fma_f32 v[160:161], v[28:29], v[124:125], v[156:157]
	v_pk_fma_f32 v[162:163], v[30:31], v[126:127], v[158:159]
	v_cvt_pk_bf16_f32 v164, v160, v161
	v_cvt_pk_bf16_f32 v165, v162, v163
	global_store_dwordx2 v170, v[164:165], s[8:9] offset:3584
	s_add_i32 s12, s12, s4
	s_cmp_lt_i32 s12, s19
	s_cbranch_scc0 .LBB0_59
.Lp1_it1:
	s_waitcnt vmcnt(8)
	s_add_i32 s14, s12, s5
	s_cmp_lt_i32 s14, s19
	s_cbranch_scc0 .Lp1_nopf1
	s_add_i32 s8, s14, 0xffffc000
	s_cmpk_lt_i32 s14, 0x4000
	s_cselect_b32 s6, s16, s20
	s_cselect_b32 s7, s17, s21
	s_cselect_b32 s8, s14, s8
	s_lshl_b32 s8, s8, 13
	s_add_u32 s6, s6, s8
	s_addc_u32 s7, s7, 0
	s_add_u32 s10, s6, 0x1000
	s_addc_u32 s11, s7, 0
	global_load_dwordx4 v[0:3], v168, s[6:7]
	global_load_dwordx4 v[4:7], v168, s[6:7] offset:1024
	global_load_dwordx4 v[8:11], v168, s[6:7] offset:2048
	global_load_dwordx4 v[12:15], v168, s[6:7] offset:3072
	global_load_dwordx4 v[16:19], v168, s[10:11]
	global_load_dwordx4 v[20:23], v168, s[10:11] offset:1024
	global_load_dwordx4 v[24:27], v168, s[10:11] offset:2048
	global_load_dwordx4 v[28:31], v168, s[10:11] offset:3072

; __device__ __forceinline__ unsigned pk2(float lo, float hi) { return f2bf(lo) | (f2bf(hi) << 16); }
;     ...
;         if (do_mod) {
;             const float* sh = modl + mv * NMOD + shc * D; const float* sc = modl + mv * NMOD + scc * D;
; #pragma unroll
;             for (int j = 0; j < 8; ++j) { const f32x4 s1 = *(const f32x4*)(sc + lane * 4 + 256 * j), h1 = *(const f32x4*)(sh + lane * 4 + 256 * j);
;                 const f32x4 a = v[j] * (s1 + 1.f) + h1; u32x2 o; o.x = pk2(a.x, a.y); o.y = pk2(a.z, a.w);
;                 *(u32x2*)(aout + (size_t)m * D + lane * 4 + 256 * j) = o; }
.Lp1_modok1:
	s_lshl_b32 s18, s12, 12
	s_add_u32 s8, s24, s18
	s_addc_u32 s9, s25, 0
	v_pk_fma_f32 v[160:161], v[32:33], v[96:97], v[128:129]
	v_pk_fma_f32 v[162:163], v[34:35], v[98:99], v[130:131]
	v_cvt_pk_bf16_f32 v164, v160, v161
	v_cvt_pk_bf16_f32 v165, v162, v163
	global_store_dwordx2 v170, v[164:165], s[8:9]
	v_pk_fma_f32 v[160:161], v[36:37], v[100:101], v[132:133]
	v_pk_fma_f32 v[162:163], v[38:39], v[102:103], v[134:135]
	v_cvt_pk_bf16_f32 v164, v160, v161
	v_cvt_pk_bf16_f32 v165, v162, v163
	global_store_dwordx2 v170, v[164:165], s[8:9] offset:512
	v_pk_fma_f32 v[160:161], v[40:41], v[104:105], v[136:137]
	v_pk_fma_f32 v[162:163], v[42:43], v[106:107], v[138:139]
	v_cvt_pk_bf16_f32 v164, v160, v161
	v_cvt_pk_bf16_f32 v165, v162, v163
	global_store_dwordx2 v170, v[164:165], s[8:9] offset:1024
	v_pk_fma_f32 v[160:161], v[44:45], v[108:109], v[140:141]
	v_pk_fma_f32 v[162:163], v[46:47], v[110:111], v[142:143]
	v_cvt_pk_bf16_f32 v164, v160, v161
	v_cvt_pk_bf16_f32 v165, v162, v163
	global_store_dwordx2 v170, v[164:165], s[8:9] offset:1536
	v_pk_fma_f32 v[160:161], v[48:49], v[112:113], v[144:145]
	v_pk_fma_f32 v[162:163], v[50:51], v[114:115], v[146:147]
	v_cvt_pk_bf16_f32 v164, v160, v161
	v_cvt_pk_bf16_f32 v165, v162, v163
	global_store_dwordx2 v170, v[164:165], s[8:9] offset:2048
	v_pk_fma_f32 v[160:161], v[52:53], v[116:117], v[148:149]
	v_pk_fma_f32 v[162:163], v[54:55], v[118:119], v[150:151]
	v_cvt_pk_bf16_f32 v164, v160, v161
	v_cvt_pk_bf16_f32 v165, v162, v163
	global_store_dwordx2 v170, v[164:165], s[8:9] offset:2560
	v_pk_fma_f32 v[160:161], v[56:57], v[120:121], v[152:153]
	v_pk_fma_f32 v[162:163], v[58:59], v[122:123], v[154:155]
	v_cvt_pk_bf16_f32 v164, v160, v161
	v_cvt_pk_bf16_f32 v165, v162, v163
	global_store_dwordx2 v170, v[164:165], s[8:9] offset:3072
	v_pk_fma_f32 v[160:161], v[60:61], v[124:125], v[156:157]
	v_pk_fma_f32 v[162:163], v[62:63], v[126:127], v[158:159]
	v_cvt_pk_bf16_f32 v164, v160, v161
	v_cvt_pk_bf16_f32 v165, v162, v163
	global_store_dwordx2 v170, v[164:165], s[8:9] offset:3584
	s_add_i32 s12, s12, s4
	s_cmp_lt_i32 s12, s19
	s_cbranch_scc0 .LBB0_59
	s_branch .Lp1_it0
